# k/v cache copy moved from the gate/up K-loop into the tile epilogues: 3 float4 per thread per tile, loads issued after the epilogue's partial-sum wait, stores at the tile-loop latch; K in phases 1+9,
# speedup vs baseline: 1.0133x; 1.0133x over previous
.LBB0_680:
	v_lshl_add_u64 v[10:11], s[8:9], 0, v[0:1]
	v_mov_b32_e32 v131, v1
	v_lshl_add_u64 v[12:13], s[8:9], 0, v[130:131]
	s_add_i32 m0, s24, 0x18000
	v_lshl_add_u64 v[10:11], v[10:11], 0, s[0:1]
	v_lshl_add_u64 v[14:15], s[10:11], 0, v[0:1]
	s_waitcnt vmcnt(2)
	s_barrier
	global_load_lds_dwordx4 v[10:11], off
	v_lshl_add_u64 v[10:11], v[12:13], 0, s[0:1]
	s_add_i32 m0, s24, 0x1a000
	s_add_i32 s28, s24, 0x8000
	s_add_i32 s29, s24, 0xa000
	v_lshl_add_u64 v[16:17], s[10:11], 0, v[130:131]
	global_load_lds_dwordx4 v[10:11], off
	v_lshl_add_u64 v[10:11], v[14:15], 0, s[0:1]
	s_mov_b32 m0, s28
	s_add_u32 s8, s8, 0x40080
	global_load_lds_dwordx4 v[10:11], off
	v_lshl_add_u64 v[10:11], v[16:17], 0, s[0:1]
	s_mov_b32 m0, s29
	s_addc_u32 s9, s9, 0
	global_load_lds_dwordx4 v[10:11], off
	s_add_i32 m0, s24, 0x1c000
	v_lshl_add_u64 v[10:11], s[8:9], 0, v[0:1]
	global_load_lds_dwordx4 v[10:11], off
	v_lshl_add_u64 v[10:11], s[8:9], 0, v[130:131]
	s_add_i32 m0, s24, 0x1e000
	s_nop 0
	global_load_lds_dwordx4 v[10:11], off
	s_waitcnt vmcnt(6)
	s_barrier
	s_and_saveexec_b64 s[8:9], s[40:41]
	v_lshl_add_u32 v9, v146, 2, 0
	v_add_u32_e32 v9, 0x21040, v9
	v_add_f32_e32 v176, v168, v169
	v_add_f32_e32 v177, v170, v171
	v_add_f32_e32 v176, v176, v177
	v_add_f32_e32 v177, v164, v165
	v_add_f32_e32 v178, v166, v167
	v_add_f32_e32 v177, v177, v178
	v_add_f32_e32 v176, v176, v177
	v_add_f32_e32 v177, v160, v161
	v_add_f32_e32 v178, v162, v163
	v_add_f32_e32 v177, v177, v178
	v_add_f32_e32 v176, v176, v177
	v_add_f32_e32 v177, v172, v173
	v_add_f32_e32 v178, v174, v175
	v_add_f32_e32 v177, v177, v178
	v_add_f32_e32 v176, v176, v177
	s_mov_b32 s98, 0x800000
	v_fmamk_f32 v176, v176, 0x3a800000, v241
	v_mul_f32_e32 v177, 0x4b800000, v176
	v_cmp_gt_f32_e32 vcc, s98, v176
	s_nop 1
	v_cndmask_b32_e32 v176, v176, v177, vcc
	v_rsq_f32_e32 v176, v176
	s_nop 0
	v_mul_f32_e32 v177, 0x45800000, v176
	v_cndmask_b32_e32 v4, v176, v177, vcc
	ds_write_b32 v9, v4
	s_or_b64 exec, exec, s[8:9]
	v_lshrrev_b32_e32 v9, 1, v146
	v_and_b32_e32 v4, 15, v146
	v_and_b32_e32 v9, 24, v9
	v_lshl_or_b32 v147, s14, 6, v4
	v_lshlrev_b32_e32 v10, 1, v9
	v_lshl_or_b32 v4, v4, 6, v10
	v_lshlrev_b32_e32 v10, 2, v147
	s_lshl_b32 s8, s14, 13
	v_and_b32_e32 v11, 32, v10
	v_bitop3_b32 v11, v4, s8, v11 bitop3:0xde
	s_lshl_b32 s8, s15, 5
	s_and_b32 s10, s8, 0x60
	v_lshlrev_b32_e32 v12, 2, v146
	s_lshl_b32 s8, s10, 7
	v_and_b32_e32 v13, 32, v12
	v_bitop3_b32 v148, v4, s8, v13 bitop3:0xde
	v_lshlrev_b32_e32 v4, 14, v5
	v_and_b32_e32 v4, 0xffff8000, v4
	v_lshl_add_u32 v3, v3, 11, v4
	v_and_b32_e32 v4, 1, v5
	v_lshl_or_b32 v3, v4, 6, v3
	v_lshl_add_u32 v4, v6, 1, v3
	v_lshlrev_b32_e32 v3, 14, v2
	s_add_i32 s11, 0, 0x21040
	v_readlane_b32 s16, v253, 46
	v_and_b32_e32 v3, 0xffff8000, v3
	s_cmpk_lt_u32 s13, 0x100
	v_readlane_b32 s18, v253, 48
	v_lshl_add_u32 v3, v7, 11, v3
	v_and_b32_e32 v2, 1, v2
	s_cselect_b64 s[8:9], -1, 0
	v_or_b32_e32 v151, s10, v9
	v_readlane_b32 s19, v253, 49
	s_add_u32 s10, s18, 0x5040080
	v_lshl_or_b32 v2, v2, 6, v3
	v_add_u32_e32 v149, s11, v12
	v_add_u32_e32 v150, s11, v10
	s_addc_u32 s11, s19, 0
	v_mov_b32_e32 v5, v1
	v_lshl_add_u32 v2, v8, 1, v2
	v_mov_b32_e32 v3, v1
	v_lshl_add_u64 v[132:133], s[10:11], 0, v[4:5]
	v_lshl_add_u64 v[134:135], s[10:11], 0, v[2:3]
	v_readlane_b32 s10, v253, 52
	s_add_u32 s10, s12, s10
	v_readlane_b32 s11, v253, 54
	s_addc_u32 s11, 0, s11
	s_add_u32 s10, s18, s10
	s_addc_u32 s11, s19, s11
	s_add_u32 s30, s10, 0x100
	v_readlane_b32 s37, v253, 3
	v_readlane_b32 s38, v253, 4
	v_readlane_b32 s18, v253, 5
	v_readlane_b32 s20, v253, 16
	s_addc_u32 s31, s11, 0
	s_mov_b32 s33, 0
	v_add_u32_e32 v152, 0, v11
	v_readlane_b32 s19, v253, 6
	v_readlane_b32 s21, v253, 17
	v_readlane_b32 s34, v251, 0
	s_mov_b32 s36, s37
	s_mov_b32 s35, s38
	v_readlane_b32 s17, v253, 47
	v_readlane_b32 s99, v253, 41
	s_mov_b64 s[100:101], 0
	v_mov_b32_e32 v226, -64
	v_mov_b32_e32 v227, -1
	s_cmp_eq_u32 s99, 1
	s_cbranch_scc1 .Lbg4_K
	s_cmp_eq_u32 s99, 11
	s_cbranch_scc1 .Lbg4_V
	v_mov_b32_e32 v226, 0x800
	v_mov_b32_e32 v227, 32
	s_cmp_eq_u32 s99, 9
	s_cbranch_scc1 .Lbg4_K
	s_cmp_eq_u32 s99, 19
	s_cbranch_scc1 .Lbg4_V
	s_branch .Lbg4_idone
.Lbg4_K:
	v_readlane_b32 s100, v253, 42
	v_readlane_b32 s101, v253, 43
	s_nop 0
	s_load_dwordx2 s[98:99], s[100:101], 0xd8
	s_load_dwordx2 s[100:101], s[100:101], 0x18
	s_waitcnt lgkmcnt(0)
	s_add_u32 s98, s98, 0x912e000
	s_addc_u32 s99, s99, 0
	s_branch .Lbg4_common
.Lbg4_V:
	v_readlane_b32 s100, v253, 42
	v_readlane_b32 s101, v253, 43
	s_nop 0
	s_load_dwordx2 s[98:99], s[100:101], 0xd8
	s_load_dwordx2 s[100:101], s[100:101], 0x20
	s_waitcnt lgkmcnt(0)
	s_add_u32 s98, s98, 0x1212e000
	s_addc_u32 s99, s99, 0
	s_branch .Lbg4_common
.Lbg4_common:
	s_add_u32 s100, s100, 0x400
	s_addc_u32 s101, s101, 0
	s_sub_u32 s98, s98, s100
	s_subb_u32 s99, s99, s101
	v_writelane_b32 v255, s98, 62
	v_writelane_b32 v255, s99, 63
	s_lshl_b32 s99, s34, 9
	v_add_u32_e32 v228, s99, v201
	v_add_u32_e32 v226, v226, v228
	v_cmp_le_i32_e32 vcc, 0x1ffc0, v226
	v_subrev_u32_e32 v228, 0x1ffc0, v226
	s_nop 0
	v_cndmask_b32_e32 v226, v226, v228, vcc
	v_cndmask_b32_e64 v228, 0, 1, vcc
	v_add_u32_e32 v227, v227, v228
.Lbg4_idone:
	s_branch .LBB0_685
	s_nop 0
	s_nop 0
	s_nop 0
	s_nop 0
	s_nop 0
	s_nop 0
	s_nop 0
	s_nop 0
	s_nop 0
	s_nop 0
	s_nop 0
	s_nop 0
	s_nop 0
	s_nop 0

.LBB0_684:
	s_cmp_eq_u64 s[100:101], 0
	s_cbranch_scc1 .Lbg4_sskip
	v_readlane_b32 s98, v255, 62
	v_readlane_b32 s99, v255, 63
	s_add_u32 s98, s98, s100
	s_addc_u32 s99, s99, s101
	s_waitcnt vmcnt(8)
	v_mov_b32_e32 v2, v226
	v_mov_b32_e32 v3, v227
	v_lshlrev_b32_e32 v4, 21, v3
	v_lshl_add_u32 v4, v2, 4, v4
	v_mov_b32_e32 v5, 0
	v_lshl_add_u64 v[4:5], s[98:99], 0, v[4:5]
	v_cmp_gt_i32_e32 vcc, 64, v3
	s_nop 1
	s_mov_b64 exec, vcc
	s_nop 0
	global_store_dwordx4 v[4:5], v[236:239], off nt
	s_mov_b64 exec, -1
	v_subrev_u32_e32 v2, 64, v2
	v_subrev_u32_e32 v3, 1, v3
	v_cmp_gt_i32_e32 vcc, 0, v2
	v_add_u32_e32 v10, 0x1ffc0, v2
	s_nop 0
	v_cndmask_b32_e32 v2, v2, v10, vcc
	v_cndmask_b32_e64 v10, 0, 1, vcc
	v_sub_u32_e32 v3, v3, v10
	v_lshlrev_b32_e32 v6, 21, v3
	v_lshl_add_u32 v6, v2, 4, v6
	v_mov_b32_e32 v7, 0
	v_lshl_add_u64 v[6:7], s[98:99], 0, v[6:7]
	v_cmp_gt_i32_e32 vcc, 64, v3
	s_nop 1
	s_mov_b64 exec, vcc
	s_nop 0
	global_store_dwordx4 v[6:7], v[232:235], off nt
	s_mov_b64 exec, -1
	v_subrev_u32_e32 v2, 64, v2
	v_subrev_u32_e32 v3, 1, v3
	v_cmp_gt_i32_e32 vcc, 0, v2
	v_add_u32_e32 v10, 0x1ffc0, v2
	s_nop 0
	v_cndmask_b32_e32 v2, v2, v10, vcc
	v_cndmask_b32_e64 v10, 0, 1, vcc
	v_sub_u32_e32 v3, v3, v10
	v_lshlrev_b32_e32 v8, 21, v3
	v_lshl_add_u32 v8, v2, 4, v8
	v_mov_b32_e32 v9, 0
	v_lshl_add_u64 v[8:9], s[98:99], 0, v[8:9]
	v_cmp_gt_i32_e32 vcc, 64, v3
	s_nop 1
	s_mov_b64 exec, vcc
	s_nop 0
	global_store_dwordx4 v[8:9], v[228:231], off nt
	s_mov_b64 exec, -1

.LBB0_693:
	s_or_b64 exec, exec, s[18:19]
	s_cmp_eq_u64 s[100:101], 0
	s_cbranch_scc1 .Lbg4_lskip
	v_add_u32_e32 v226, 64, v226
	v_add_u32_e32 v227, 1, v227
	v_cmp_le_i32_e32 vcc, 0x1ffc0, v226
	v_subrev_u32_e32 v228, 0x1ffc0, v226
	s_nop 0
	v_cndmask_b32_e32 v226, v226, v228, vcc
	v_cndmask_b32_e64 v228, 0, 1, vcc
	v_add_u32_e32 v227, v227, v228
	v_lshlrev_b32_e32 v228, 21, v227
	v_lshl_add_u32 v228, v226, 4, v228
	v_mov_b32_e32 v229, 0
	v_lshl_add_u64 v[228:229], s[100:101], 0, v[228:229]
	v_cmp_gt_i32_e32 vcc, 64, v227
	s_nop 1
	s_mov_b64 exec, vcc
	s_nop 0
	global_load_dwordx4 v[228:231], v[228:229], off nt
	s_mov_b64 exec, -1
	v_add_u32_e32 v226, 64, v226
	v_add_u32_e32 v227, 1, v227
	v_cmp_le_i32_e32 vcc, 0x1ffc0, v226
	v_subrev_u32_e32 v232, 0x1ffc0, v226
	s_nop 0
	v_cndmask_b32_e32 v226, v226, v232, vcc
	v_cndmask_b32_e64 v232, 0, 1, vcc
	v_add_u32_e32 v227, v227, v232
	v_lshlrev_b32_e32 v232, 21, v227
	v_lshl_add_u32 v232, v226, 4, v232
	v_mov_b32_e32 v233, 0
	v_lshl_add_u64 v[232:233], s[100:101], 0, v[232:233]
	v_cmp_gt_i32_e32 vcc, 64, v227
	s_nop 1
	s_mov_b64 exec, vcc
	s_nop 0
	global_load_dwordx4 v[232:235], v[232:233], off nt
	s_mov_b64 exec, -1
	v_add_u32_e32 v226, 64, v226
	v_add_u32_e32 v227, 1, v227
	v_cmp_le_i32_e32 vcc, 0x1ffc0, v226
	v_subrev_u32_e32 v236, 0x1ffc0, v226
	s_nop 0
	v_cndmask_b32_e32 v226, v226, v236, vcc
	v_cndmask_b32_e64 v236, 0, 1, vcc
	v_add_u32_e32 v227, v227, v236
	v_lshlrev_b32_e32 v236, 21, v227
	v_lshl_add_u32 v236, v226, 4, v236
	v_mov_b32_e32 v237, 0
	v_lshl_add_u64 v[236:237], s[100:101], 0, v[236:237]
	v_cmp_gt_i32_e32 vcc, 64, v227
	s_nop 1
	s_mov_b64 exec, vcc
	s_nop 0
	global_load_dwordx4 v[236:239], v[236:237], off nt
	s_mov_b64 exec, -1
.Lbg4_lskip:
	v_lshl_add_u32 v136, s33, 10, v150
	ds_read2_b32 v[142:143], v136 offset1:16
	ds_read2_b32 v[140:141], v136 offset0:32 offset1:48
	ds_read2_b32 v[138:139], v136 offset0:128 offset1:144
	ds_read2_b32 v[136:137], v136 offset0:160 offset1:176
	v_readlane_b32 s16, v254, 1
	s_waitcnt lgkmcnt(0)
	v_pk_mul_f32 v[126:127], v[126:127], v[142:143] op_sel_hi:[1,0]
	v_pk_mul_f32 v[128:129], v[128:129], v[142:143] op_sel_hi:[1,0]
	v_pk_mul_f32 v[120:121], v[120:121], v[142:143] op_sel_hi:[1,0]
	v_pk_mul_f32 v[118:119], v[118:119], v[142:143] op_sel_hi:[1,0]
	v_pk_mul_f32 v[124:125], v[124:125], v[142:143] op_sel_hi:[1,0]
	v_pk_mul_f32 v[122:123], v[122:123], v[142:143] op_sel_hi:[1,0]
	v_pk_mul_f32 v[116:117], v[116:117], v[142:143] op_sel_hi:[1,0]
	v_pk_mul_f32 v[114:115], v[114:115], v[142:143] op_sel_hi:[1,0]
	v_mul_f32_e32 v142, 0xbfb8aa3b, v126
	v_exp_f32_e32 v142, v142
	v_lshl_or_b32 v144, s38, 7, v151
	v_readlane_b32 s17, v254, 2
	v_lshl_add_u32 v154, s37, 8, v147
	v_add_f32_e32 v142, 1.0, v142
	v_rcp_f32_e32 v142, v142
	v_ashrrev_i32_e32 v145, 31, v144
	s_movk_i32 s18, 0x1600
	v_pk_mul_f32 v[94:95], v[94:95], v[140:141] op_sel_hi:[1,0]
	v_mul_f32_e32 v126, v126, v142
	v_mul_f32_e32 v118, v118, v126
	v_mul_f32_e32 v126, 0xbfb8aa3b, v127
	v_exp_f32_e32 v126, v126
	v_pk_mul_f32 v[86:87], v[86:87], v[140:141] op_sel_hi:[1,0]
	v_pk_mul_f32 v[96:97], v[96:97], v[140:141] op_sel_hi:[1,0]
	v_pk_mul_f32 v[88:89], v[88:89], v[140:141] op_sel_hi:[1,0]
	v_add_f32_e32 v126, 1.0, v126
	v_rcp_f32_e32 v126, v126
	v_pk_mul_f32 v[90:91], v[90:91], v[140:141] op_sel_hi:[1,0]
	v_pk_mul_f32 v[92:93], v[92:93], v[140:141] op_sel_hi:[1,0]
	v_pk_mul_f32 v[62:63], v[62:63], v[138:139] op_sel_hi:[1,0]
	v_mul_f32_e32 v126, v127, v126
	v_mul_f32_e32 v119, v119, v126
	v_cvt_pk_bf16_f32 v118, v118, v119
	v_mul_f32_e32 v119, 0xbfb8aa3b, v128
	v_exp_f32_e32 v119, v119
	v_pk_mul_f32 v[54:55], v[54:55], v[138:139] op_sel_hi:[1,0]
	v_pk_mul_f32 v[64:65], v[64:65], v[138:139] op_sel_hi:[1,0]
	v_pk_mul_f32 v[56:57], v[56:57], v[138:139] op_sel_hi:[1,0]
	v_add_f32_e32 v119, 1.0, v119
	v_rcp_f32_e32 v119, v119
	v_pk_mul_f32 v[58:59], v[58:59], v[138:139] op_sel_hi:[1,0]
	v_pk_mul_f32 v[60:61], v[60:61], v[138:139] op_sel_hi:[1,0]
	v_pk_mul_f32 v[30:31], v[30:31], v[136:137] op_sel_hi:[1,0]
	v_mul_f32_e32 v119, v128, v119
	v_mul_f32_e32 v119, v120, v119
	v_mul_f32_e32 v120, 0xbfb8aa3b, v129
	v_exp_f32_e32 v120, v120
	v_pk_mul_f32 v[22:23], v[22:23], v[136:137] op_sel_hi:[1,0]
	v_pk_mul_f32 v[32:33], v[32:33], v[136:137] op_sel_hi:[1,0]
	v_pk_mul_f32 v[24:25], v[24:25], v[136:137] op_sel_hi:[1,0]
	v_add_f32_e32 v120, 1.0, v120
	v_rcp_f32_e32 v120, v120
	v_pk_mul_f32 v[26:27], v[26:27], v[136:137] op_sel_hi:[1,0]
	v_pk_mul_f32 v[28:29], v[28:29], v[136:137] op_sel_hi:[1,0]
	v_mul_f32_e32 v120, v129, v120
	v_mul_f32_e32 v120, v121, v120
	v_cvt_pk_bf16_f32 v119, v119, v120
	v_mul_f32_e32 v120, 0xbfb8aa3b, v122
	v_exp_f32_e32 v120, v120
	s_nop 0
	v_add_f32_e32 v120, 1.0, v120
	v_rcp_f32_e32 v120, v120
	s_nop 0
	v_mul_f32_e32 v120, v122, v120
	v_mul_f32_e32 v114, v114, v120
	v_mul_f32_e32 v120, 0xbfb8aa3b, v123
	v_exp_f32_e32 v120, v120
	s_nop 0
	v_add_f32_e32 v120, 1.0, v120
	v_rcp_f32_e32 v120, v120
	s_nop 0
	v_mul_f32_e32 v120, v123, v120
	v_mul_f32_e32 v115, v115, v120
	v_cvt_pk_bf16_f32 v120, v114, v115
	v_mul_f32_e32 v114, 0xbfb8aa3b, v124
	v_mul_f32_e32 v115, 0xbfb8aa3b, v125
	v_exp_f32_e32 v114, v114
	v_exp_f32_e32 v115, v115
	v_add_f32_e32 v114, 1.0, v114
	v_add_f32_e32 v115, 1.0, v115
	v_rcp_f32_e32 v114, v114
	v_rcp_f32_e32 v115, v115
	v_mul_f32_e32 v114, v124, v114
	v_mul_f32_e32 v115, v125, v115
	v_mul_f32_e32 v114, v116, v114
	v_mul_f32_e32 v115, v117, v115
	v_cvt_pk_bf16_f32 v121, v114, v115
	v_mov_b64_e32 v[114:115], s[16:17]
	v_mad_i64_i32 v[122:123], s[16:17], v154, s18, v[114:115]
	v_lshlrev_b64 v[116:117], 1, v[144:145]
	v_lshl_add_u64 v[122:123], v[122:123], 0, v[116:117]
	global_store_dwordx4 v[122:123], v[118:121], off
	s_nop 1
	v_or_b32_e32 v119, 16, v154
	v_mov_b32_e32 v118, v143
	v_pk_mul_f32 v[110:111], v[110:111], v[118:119] op_sel_hi:[1,0]
	v_pk_mul_f32 v[120:121], v[100:101], v[118:119] op_sel_hi:[1,0]
	v_pk_mul_f32 v[100:101], v[98:99], v[118:119] op_sel_hi:[1,0]
	v_mul_f32_e32 v98, 0xbfb8aa3b, v110
	v_mul_f32_e32 v99, 0xbfb8aa3b, v111
	v_exp_f32_e32 v98, v98
	v_exp_f32_e32 v99, v99
	v_pk_mul_f32 v[102:103], v[102:103], v[118:119] op_sel_hi:[1,0]
	v_pk_mul_f32 v[112:113], v[112:113], v[118:119] op_sel_hi:[1,0]
	v_add_f32_e32 v98, 1.0, v98
	v_add_f32_e32 v99, 1.0, v99
	v_rcp_f32_e32 v98, v98
	v_rcp_f32_e32 v99, v99
	v_pk_mul_f32 v[104:105], v[104:105], v[118:119] op_sel_hi:[1,0]
	v_pk_mul_f32 v[106:107], v[106:107], v[118:119] op_sel_hi:[1,0]
	v_mul_f32_e32 v98, v110, v98
	v_mul_f32_e32 v99, v111, v99
	v_mul_f32_e32 v98, v102, v98
	v_mul_f32_e32 v99, v103, v99
	v_cvt_pk_bf16_f32 v98, v98, v99
	v_mul_f32_e32 v99, 0xbfb8aa3b, v112
	v_mul_f32_e32 v102, 0xbfb8aa3b, v113
	v_exp_f32_e32 v99, v99
	v_exp_f32_e32 v102, v102
	v_pk_mul_f32 v[108:109], v[108:109], v[118:119] op_sel_hi:[1,0]
	v_add_f32_e32 v99, 1.0, v99
	v_add_f32_e32 v102, 1.0, v102
	v_rcp_f32_e32 v99, v99
	v_rcp_f32_e32 v102, v102
	v_mul_f32_e32 v99, v112, v99
	v_mul_f32_e32 v102, v113, v102
	v_mul_f32_e32 v99, v104, v99
	v_mul_f32_e32 v102, v105, v102
	v_cvt_pk_bf16_f32 v99, v99, v102
	v_mul_f32_e32 v102, 0xbfb8aa3b, v106
	v_exp_f32_e32 v102, v102
	s_nop 0
	v_add_f32_e32 v102, 1.0, v102
	v_rcp_f32_e32 v102, v102
	s_nop 0
	v_mul_f32_e32 v102, v106, v102
	v_mul_f32_e32 v100, v100, v102
	v_mul_f32_e32 v102, 0xbfb8aa3b, v107
	v_exp_f32_e32 v102, v102
	s_nop 0
	v_add_f32_e32 v102, 1.0, v102
	v_rcp_f32_e32 v102, v102
	s_nop 0
	v_mul_f32_e32 v102, v107, v102
	v_mul_f32_e32 v101, v101, v102
	v_cvt_pk_bf16_f32 v100, v100, v101
	v_mul_f32_e32 v101, 0xbfb8aa3b, v108
	v_mul_f32_e32 v102, 0xbfb8aa3b, v109
	v_exp_f32_e32 v101, v101
	v_exp_f32_e32 v102, v102
	v_add_f32_e32 v101, 1.0, v101
	v_add_f32_e32 v102, 1.0, v102
	v_rcp_f32_e32 v101, v101
	v_rcp_f32_e32 v102, v102
	v_mul_f32_e32 v101, v108, v101
	v_mul_f32_e32 v102, v109, v102
	v_mul_f32_e32 v101, v120, v101
	v_mul_f32_e32 v102, v121, v102
	v_cvt_pk_bf16_f32 v101, v101, v102
	v_mad_i64_i32 v[102:103], s[16:17], v119, s18, v[114:115]
	v_lshl_add_u64 v[102:103], v[102:103], 0, v[116:117]
	global_store_dwordx4 v[102:103], v[98:101], off
	s_nop 1
	v_pk_mul_f32 v[98:99], v[84:85], v[140:141] op_sel_hi:[1,0]
	v_pk_mul_f32 v[84:85], v[82:83], v[140:141] op_sel_hi:[1,0]
	v_mul_f32_e32 v82, 0xbfb8aa3b, v94
	v_mul_f32_e32 v83, 0xbfb8aa3b, v95
	v_exp_f32_e32 v82, v82
	v_exp_f32_e32 v83, v83
	v_or_b32_e32 v100, 32, v154
	v_add_f32_e32 v82, 1.0, v82
	v_add_f32_e32 v83, 1.0, v83
	v_rcp_f32_e32 v82, v82
	v_rcp_f32_e32 v83, v83
	v_mul_f32_e32 v82, v94, v82
	v_mul_f32_e32 v83, v95, v83
	v_mul_f32_e32 v82, v86, v82
	v_mul_f32_e32 v83, v87, v83
	v_cvt_pk_bf16_f32 v82, v82, v83
	v_mul_f32_e32 v83, 0xbfb8aa3b, v96
	v_mul_f32_e32 v86, 0xbfb8aa3b, v97
	v_exp_f32_e32 v83, v83
	v_exp_f32_e32 v86, v86
	v_add_f32_e32 v83, 1.0, v83
	v_add_f32_e32 v86, 1.0, v86
	v_rcp_f32_e32 v83, v83
	v_rcp_f32_e32 v86, v86
	v_mul_f32_e32 v83, v96, v83
	v_mul_f32_e32 v86, v97, v86
	v_mul_f32_e32 v83, v88, v83
	v_mul_f32_e32 v86, v89, v86
	v_cvt_pk_bf16_f32 v83, v83, v86
	v_mul_f32_e32 v86, 0xbfb8aa3b, v90
	v_exp_f32_e32 v86, v86
	s_nop 0
	v_add_f32_e32 v86, 1.0, v86
	v_rcp_f32_e32 v86, v86
	s_nop 0
	v_mul_f32_e32 v86, v90, v86
	v_mul_f32_e32 v84, v84, v86
	v_mul_f32_e32 v86, 0xbfb8aa3b, v91
	v_exp_f32_e32 v86, v86
	s_nop 0
	v_add_f32_e32 v86, 1.0, v86
	v_rcp_f32_e32 v86, v86
	s_nop 0
	v_mul_f32_e32 v86, v91, v86
	v_mul_f32_e32 v85, v85, v86
	v_cvt_pk_bf16_f32 v84, v84, v85
	v_mul_f32_e32 v85, 0xbfb8aa3b, v92
	v_mul_f32_e32 v86, 0xbfb8aa3b, v93
	v_exp_f32_e32 v85, v85
	v_exp_f32_e32 v86, v86
	v_add_f32_e32 v85, 1.0, v85
	v_add_f32_e32 v86, 1.0, v86
	v_rcp_f32_e32 v85, v85
	v_rcp_f32_e32 v86, v86
	v_mul_f32_e32 v85, v92, v85
	v_mul_f32_e32 v86, v93, v86
	v_mul_f32_e32 v85, v98, v85
	v_mul_f32_e32 v86, v99, v86
	v_cvt_pk_bf16_f32 v85, v85, v86
	v_mad_i64_i32 v[86:87], s[16:17], v100, s18, v[114:115]
	v_lshl_add_u64 v[86:87], v[86:87], 0, v[116:117]
	global_store_dwordx4 v[86:87], v[82:85], off
	s_nop 1
	v_or_b32_e32 v83, 48, v154
	v_mov_b32_e32 v82, v141
	v_pk_mul_f32 v[78:79], v[78:79], v[82:83] op_sel_hi:[1,0]
	v_pk_mul_f32 v[84:85], v[68:69], v[82:83] op_sel_hi:[1,0]
	v_pk_mul_f32 v[68:69], v[66:67], v[82:83] op_sel_hi:[1,0]
	v_mul_f32_e32 v66, 0xbfb8aa3b, v78
	v_mul_f32_e32 v67, 0xbfb8aa3b, v79
	v_exp_f32_e32 v66, v66
	v_exp_f32_e32 v67, v67
	v_pk_mul_f32 v[70:71], v[70:71], v[82:83] op_sel_hi:[1,0]
	v_pk_mul_f32 v[80:81], v[80:81], v[82:83] op_sel_hi:[1,0]
	v_add_f32_e32 v66, 1.0, v66
	v_add_f32_e32 v67, 1.0, v67
	v_rcp_f32_e32 v66, v66
	v_rcp_f32_e32 v67, v67
	v_pk_mul_f32 v[72:73], v[72:73], v[82:83] op_sel_hi:[1,0]
	v_pk_mul_f32 v[74:75], v[74:75], v[82:83] op_sel_hi:[1,0]
	v_mul_f32_e32 v66, v78, v66
	v_mul_f32_e32 v67, v79, v67
	v_mul_f32_e32 v66, v70, v66
	v_mul_f32_e32 v67, v71, v67
	v_cvt_pk_bf16_f32 v66, v66, v67
	v_mul_f32_e32 v67, 0xbfb8aa3b, v80
	v_mul_f32_e32 v70, 0xbfb8aa3b, v81
	v_exp_f32_e32 v67, v67
	v_exp_f32_e32 v70, v70
	v_pk_mul_f32 v[76:77], v[76:77], v[82:83] op_sel_hi:[1,0]
	v_add_f32_e32 v67, 1.0, v67
	v_add_f32_e32 v70, 1.0, v70
	v_rcp_f32_e32 v67, v67
	v_rcp_f32_e32 v70, v70
	v_mul_f32_e32 v67, v80, v67
	v_mul_f32_e32 v70, v81, v70
	v_mul_f32_e32 v67, v72, v67
	v_mul_f32_e32 v70, v73, v70
	v_cvt_pk_bf16_f32 v67, v67, v70
	v_mul_f32_e32 v70, 0xbfb8aa3b, v74
	v_exp_f32_e32 v70, v70
	s_nop 0
	v_add_f32_e32 v70, 1.0, v70
	v_rcp_f32_e32 v70, v70
	s_nop 0
	v_mul_f32_e32 v70, v74, v70
	v_mul_f32_e32 v68, v68, v70
	v_mul_f32_e32 v70, 0xbfb8aa3b, v75
	v_exp_f32_e32 v70, v70
	s_nop 0
	v_add_f32_e32 v70, 1.0, v70
	v_rcp_f32_e32 v70, v70
	s_nop 0
	v_mul_f32_e32 v70, v75, v70
	v_mul_f32_e32 v69, v69, v70
	v_cvt_pk_bf16_f32 v68, v68, v69
	v_mul_f32_e32 v69, 0xbfb8aa3b, v76
	v_mul_f32_e32 v70, 0xbfb8aa3b, v77
	v_exp_f32_e32 v69, v69
	v_exp_f32_e32 v70, v70
	v_add_f32_e32 v69, 1.0, v69
	v_add_f32_e32 v70, 1.0, v70
	v_rcp_f32_e32 v69, v69
	v_rcp_f32_e32 v70, v70
	v_mul_f32_e32 v69, v76, v69
	v_mul_f32_e32 v70, v77, v70
	v_mul_f32_e32 v69, v84, v69
	v_mul_f32_e32 v70, v85, v70
	v_cvt_pk_bf16_f32 v69, v69, v70
	v_mad_i64_i32 v[70:71], s[16:17], v83, s18, v[114:115]
	v_lshl_add_u64 v[70:71], v[70:71], 0, v[116:117]
	global_store_dwordx4 v[70:71], v[66:69], off
	s_nop 1
	v_pk_mul_f32 v[66:67], v[52:53], v[138:139] op_sel_hi:[1,0]
	v_pk_mul_f32 v[52:53], v[50:51], v[138:139] op_sel_hi:[1,0]
	v_mul_f32_e32 v50, 0xbfb8aa3b, v62
	v_mul_f32_e32 v51, 0xbfb8aa3b, v63
	v_exp_f32_e32 v50, v50
	v_exp_f32_e32 v51, v51
	v_add_u32_e32 v68, 0x80, v154
	v_add_f32_e32 v50, 1.0, v50
	v_add_f32_e32 v51, 1.0, v51
	v_rcp_f32_e32 v50, v50
	v_rcp_f32_e32 v51, v51
	v_mul_f32_e32 v50, v62, v50
	v_mul_f32_e32 v51, v63, v51
	v_mul_f32_e32 v50, v54, v50
	v_mul_f32_e32 v51, v55, v51
	v_cvt_pk_bf16_f32 v50, v50, v51
	v_mul_f32_e32 v51, 0xbfb8aa3b, v64
	v_mul_f32_e32 v54, 0xbfb8aa3b, v65
	v_exp_f32_e32 v51, v51
	v_exp_f32_e32 v54, v54
	v_add_f32_e32 v51, 1.0, v51
	v_add_f32_e32 v54, 1.0, v54
	v_rcp_f32_e32 v51, v51
	v_rcp_f32_e32 v54, v54
	v_mul_f32_e32 v51, v64, v51
	v_mul_f32_e32 v54, v65, v54
	v_mul_f32_e32 v51, v56, v51
	v_mul_f32_e32 v54, v57, v54
	v_cvt_pk_bf16_f32 v51, v51, v54
	v_mul_f32_e32 v54, 0xbfb8aa3b, v58
	v_exp_f32_e32 v54, v54
	s_nop 0
	v_add_f32_e32 v54, 1.0, v54
	v_rcp_f32_e32 v54, v54
	s_nop 0
	v_mul_f32_e32 v54, v58, v54
	v_mul_f32_e32 v52, v52, v54
	v_mul_f32_e32 v54, 0xbfb8aa3b, v59
	v_exp_f32_e32 v54, v54
	s_nop 0
	v_add_f32_e32 v54, 1.0, v54
	v_rcp_f32_e32 v54, v54
	s_nop 0
	v_mul_f32_e32 v54, v59, v54
	v_mul_f32_e32 v53, v53, v54
	v_cvt_pk_bf16_f32 v52, v52, v53
	v_mul_f32_e32 v53, 0xbfb8aa3b, v60
	v_mul_f32_e32 v54, 0xbfb8aa3b, v61
	v_exp_f32_e32 v53, v53
	v_exp_f32_e32 v54, v54
	v_add_f32_e32 v53, 1.0, v53
	v_add_f32_e32 v54, 1.0, v54
	v_rcp_f32_e32 v53, v53
	v_rcp_f32_e32 v54, v54
	v_mul_f32_e32 v53, v60, v53
	v_mul_f32_e32 v54, v61, v54
	v_mul_f32_e32 v53, v66, v53
	v_mul_f32_e32 v54, v67, v54
	v_cvt_pk_bf16_f32 v53, v53, v54
	v_mad_i64_i32 v[54:55], s[16:17], v68, s18, v[114:115]
	v_lshl_add_u64 v[54:55], v[54:55], 0, v[116:117]
	global_store_dwordx4 v[54:55], v[50:53], off
	s_nop 1
	v_add_u32_e32 v51, 0x90, v154
	v_mov_b32_e32 v50, v139
	v_pk_mul_f32 v[46:47], v[46:47], v[50:51] op_sel_hi:[1,0]
	v_pk_mul_f32 v[52:53], v[36:37], v[50:51] op_sel_hi:[1,0]
	v_pk_mul_f32 v[36:37], v[34:35], v[50:51] op_sel_hi:[1,0]
	v_mul_f32_e32 v34, 0xbfb8aa3b, v46
	v_mul_f32_e32 v35, 0xbfb8aa3b, v47
	v_exp_f32_e32 v34, v34
	v_exp_f32_e32 v35, v35
	v_pk_mul_f32 v[38:39], v[38:39], v[50:51] op_sel_hi:[1,0]
	v_pk_mul_f32 v[48:49], v[48:49], v[50:51] op_sel_hi:[1,0]
	v_add_f32_e32 v34, 1.0, v34
	v_add_f32_e32 v35, 1.0, v35
	v_rcp_f32_e32 v34, v34
	v_rcp_f32_e32 v35, v35
	v_pk_mul_f32 v[40:41], v[40:41], v[50:51] op_sel_hi:[1,0]
	v_pk_mul_f32 v[42:43], v[42:43], v[50:51] op_sel_hi:[1,0]
	v_mul_f32_e32 v34, v46, v34
	v_mul_f32_e32 v35, v47, v35
	v_mul_f32_e32 v34, v38, v34
	v_mul_f32_e32 v35, v39, v35
	v_cvt_pk_bf16_f32 v34, v34, v35
	v_mul_f32_e32 v35, 0xbfb8aa3b, v48
	v_mul_f32_e32 v38, 0xbfb8aa3b, v49
	v_exp_f32_e32 v35, v35
	v_exp_f32_e32 v38, v38
	v_pk_mul_f32 v[44:45], v[44:45], v[50:51] op_sel_hi:[1,0]
	v_add_f32_e32 v35, 1.0, v35
	v_add_f32_e32 v38, 1.0, v38
	v_rcp_f32_e32 v35, v35
	v_rcp_f32_e32 v38, v38
	v_mul_f32_e32 v35, v48, v35
	v_mul_f32_e32 v38, v49, v38
	v_mul_f32_e32 v35, v40, v35
	v_mul_f32_e32 v38, v41, v38
	v_cvt_pk_bf16_f32 v35, v35, v38
	v_mul_f32_e32 v38, 0xbfb8aa3b, v42
	v_exp_f32_e32 v38, v38
	s_nop 0
	v_add_f32_e32 v38, 1.0, v38
	v_rcp_f32_e32 v38, v38
	s_nop 0
	v_mul_f32_e32 v38, v42, v38
	v_mul_f32_e32 v36, v36, v38
	v_mul_f32_e32 v38, 0xbfb8aa3b, v43
	v_exp_f32_e32 v38, v38
	s_nop 0
	v_add_f32_e32 v38, 1.0, v38
	v_rcp_f32_e32 v38, v38
	s_nop 0
	v_mul_f32_e32 v38, v43, v38
	v_mul_f32_e32 v37, v37, v38
	v_cvt_pk_bf16_f32 v36, v36, v37
	v_mul_f32_e32 v37, 0xbfb8aa3b, v44
	v_mul_f32_e32 v38, 0xbfb8aa3b, v45
	v_exp_f32_e32 v37, v37
	v_exp_f32_e32 v38, v38
	v_add_f32_e32 v37, 1.0, v37
	v_add_f32_e32 v38, 1.0, v38
	v_rcp_f32_e32 v37, v37
	v_rcp_f32_e32 v38, v38
	v_mul_f32_e32 v37, v44, v37
	v_mul_f32_e32 v38, v45, v38
	v_mul_f32_e32 v37, v52, v37
	v_mul_f32_e32 v38, v53, v38
	v_cvt_pk_bf16_f32 v37, v37, v38
	v_mad_i64_i32 v[38:39], s[16:17], v51, s18, v[114:115]
	v_lshl_add_u64 v[38:39], v[38:39], 0, v[116:117]
	global_store_dwordx4 v[38:39], v[34:37], off
	s_nop 1
	v_pk_mul_f32 v[34:35], v[20:21], v[136:137] op_sel_hi:[1,0]
	v_pk_mul_f32 v[20:21], v[18:19], v[136:137] op_sel_hi:[1,0]
	v_mul_f32_e32 v18, 0xbfb8aa3b, v30
	v_mul_f32_e32 v19, 0xbfb8aa3b, v31
	v_exp_f32_e32 v18, v18
	v_exp_f32_e32 v19, v19
	v_add_u32_e32 v36, 0xa0, v154
	v_add_f32_e32 v18, 1.0, v18
	v_add_f32_e32 v19, 1.0, v19
	v_rcp_f32_e32 v18, v18
	v_rcp_f32_e32 v19, v19
	v_mul_f32_e32 v18, v30, v18
	v_mul_f32_e32 v19, v31, v19
	v_mul_f32_e32 v18, v22, v18
	v_mul_f32_e32 v19, v23, v19
	v_cvt_pk_bf16_f32 v18, v18, v19
	v_mul_f32_e32 v19, 0xbfb8aa3b, v32
	v_mul_f32_e32 v22, 0xbfb8aa3b, v33
	v_exp_f32_e32 v19, v19
	v_exp_f32_e32 v22, v22
	v_add_f32_e32 v19, 1.0, v19
	v_add_f32_e32 v22, 1.0, v22
	v_rcp_f32_e32 v19, v19
	v_rcp_f32_e32 v22, v22
	v_mul_f32_e32 v19, v32, v19
	v_mul_f32_e32 v22, v33, v22
	v_mul_f32_e32 v19, v24, v19
	v_mul_f32_e32 v22, v25, v22
	v_cvt_pk_bf16_f32 v19, v19, v22
	v_mul_f32_e32 v22, 0xbfb8aa3b, v26
	v_exp_f32_e32 v22, v22
	s_nop 0
	v_add_f32_e32 v22, 1.0, v22
	v_rcp_f32_e32 v22, v22
	s_nop 0
	v_mul_f32_e32 v22, v26, v22
	v_mul_f32_e32 v20, v20, v22
	v_mul_f32_e32 v22, 0xbfb8aa3b, v27
	v_exp_f32_e32 v22, v22
	s_nop 0
	v_add_f32_e32 v22, 1.0, v22
	v_rcp_f32_e32 v22, v22
	s_nop 0
	v_mul_f32_e32 v22, v27, v22
	v_mul_f32_e32 v21, v21, v22
	v_cvt_pk_bf16_f32 v20, v20, v21
	v_mul_f32_e32 v21, 0xbfb8aa3b, v28
	v_mul_f32_e32 v22, 0xbfb8aa3b, v29
	v_exp_f32_e32 v21, v21
	v_exp_f32_e32 v22, v22
	v_add_f32_e32 v21, 1.0, v21
	v_add_f32_e32 v22, 1.0, v22
	v_rcp_f32_e32 v21, v21
	v_rcp_f32_e32 v22, v22
	v_mul_f32_e32 v21, v28, v21
	v_mul_f32_e32 v22, v29, v22
	v_mul_f32_e32 v21, v34, v21
	v_mul_f32_e32 v22, v35, v22
	v_cvt_pk_bf16_f32 v21, v21, v22
	v_mad_i64_i32 v[22:23], s[16:17], v36, s18, v[114:115]
	v_lshl_add_u64 v[22:23], v[22:23], 0, v[116:117]
	global_store_dwordx4 v[22:23], v[18:21], off
	s_nop 1
	v_add_u32_e32 v19, 0xb0, v154
	v_mov_b32_e32 v18, v137
	v_pk_mul_f32 v[14:15], v[14:15], v[18:19] op_sel_hi:[1,0]
	v_pk_mul_f32 v[20:21], v[4:5], v[18:19] op_sel_hi:[1,0]
	v_pk_mul_f32 v[4:5], v[2:3], v[18:19] op_sel_hi:[1,0]
	v_mul_f32_e32 v2, 0xbfb8aa3b, v14
	v_mul_f32_e32 v3, 0xbfb8aa3b, v15
	v_exp_f32_e32 v2, v2
	v_exp_f32_e32 v3, v3
	v_pk_mul_f32 v[6:7], v[6:7], v[18:19] op_sel_hi:[1,0]
	v_pk_mul_f32 v[16:17], v[16:17], v[18:19] op_sel_hi:[1,0]
	v_add_f32_e32 v2, 1.0, v2
	v_add_f32_e32 v3, 1.0, v3
	v_rcp_f32_e32 v2, v2
	v_rcp_f32_e32 v3, v3
	v_pk_mul_f32 v[8:9], v[8:9], v[18:19] op_sel_hi:[1,0]
	v_pk_mul_f32 v[10:11], v[10:11], v[18:19] op_sel_hi:[1,0]
	v_mul_f32_e32 v2, v14, v2
	v_mul_f32_e32 v3, v15, v3
	v_mul_f32_e32 v2, v6, v2
	v_mul_f32_e32 v3, v7, v3
	v_cvt_pk_bf16_f32 v2, v2, v3
	v_mul_f32_e32 v3, 0xbfb8aa3b, v16
	v_mul_f32_e32 v6, 0xbfb8aa3b, v17
	v_exp_f32_e32 v3, v3
	v_exp_f32_e32 v6, v6
	v_pk_mul_f32 v[12:13], v[12:13], v[18:19] op_sel_hi:[1,0]
	v_add_f32_e32 v3, 1.0, v3
	v_add_f32_e32 v6, 1.0, v6
	v_rcp_f32_e32 v3, v3
	v_rcp_f32_e32 v6, v6
	v_mul_f32_e32 v3, v16, v3
	v_mul_f32_e32 v6, v17, v6
	v_mul_f32_e32 v3, v8, v3
	v_mul_f32_e32 v6, v9, v6
	v_cvt_pk_bf16_f32 v3, v3, v6
	v_mul_f32_e32 v6, 0xbfb8aa3b, v10
	v_exp_f32_e32 v6, v6
	s_nop 0
	v_add_f32_e32 v6, 1.0, v6
	v_rcp_f32_e32 v6, v6
	s_nop 0
	v_mul_f32_e32 v6, v10, v6
	v_mul_f32_e32 v4, v4, v6
	v_mul_f32_e32 v6, 0xbfb8aa3b, v11
	v_exp_f32_e32 v6, v6
	s_nop 0
	v_add_f32_e32 v6, 1.0, v6
	v_rcp_f32_e32 v6, v6
	s_nop 0
	v_mul_f32_e32 v6, v11, v6
	v_mul_f32_e32 v5, v5, v6
	v_cvt_pk_bf16_f32 v4, v4, v5
	v_mul_f32_e32 v5, 0xbfb8aa3b, v12
	v_mul_f32_e32 v6, 0xbfb8aa3b, v13
	v_exp_f32_e32 v5, v5
	v_exp_f32_e32 v6, v6
	v_add_f32_e32 v5, 1.0, v5
	v_add_f32_e32 v6, 1.0, v6
	v_rcp_f32_e32 v5, v5
	v_rcp_f32_e32 v6, v6
	v_mul_f32_e32 v5, v12, v5
	v_mul_f32_e32 v6, v13, v6
	v_mul_f32_e32 v5, v20, v5
	v_mul_f32_e32 v6, v21, v6
	v_cvt_pk_bf16_f32 v5, v5, v6
	v_mad_i64_i32 v[6:7], s[16:17], v19, s18, v[114:115]
	v_lshl_add_u64 v[6:7], v[6:7], 0, v[116:117]
	global_store_dwordx4 v[6:7], v[2:5], off
	s_andn2_b64 vcc, exec, s[10:11]
	s_mov_b64 s[10:11], -1
	s_cbranch_vccnz .LBB0_684
	s_and_saveexec_b64 s[10:11], s[40:41]
	s_lshl_b32 s16, s33, 8
	s_xor_b32 s16, s16, 0x100
	v_lshl_add_u32 v2, s16, 2, v149
	ds_write_b32 v2, v153
	s_or_b64 exec, exec, s[10:11]
	s_andn2_b64 vcc, exec, s[4:5]
	s_cbranch_vccnz .LBB0_683
	s_barrier
	s_branch .LBB0_683

.LBB0_710:
	s_or_b64 exec, exec, s[8:9]
	v_lshlrev_b32_e32 v10, 16, v6
	v_and_b32_e32 v6, 0xffff0000, v6
	v_mul_f32_e32 v6, v6, v6
	v_fmac_f32_e32 v6, v10, v10
	v_lshlrev_b32_e32 v10, 16, v7
	v_fmac_f32_e32 v6, v10, v10
	v_and_b32_e32 v7, 0xffff0000, v7
	v_fmac_f32_e32 v6, v7, v7
	v_lshlrev_b32_e32 v7, 16, v8
	v_fmac_f32_e32 v6, v7, v7
	v_and_b32_e32 v7, 0xffff0000, v8
	v_fmac_f32_e32 v6, v7, v7
	v_lshlrev_b32_e32 v7, 16, v9
	v_fmac_f32_e32 v6, v7, v7
	v_and_b32_e32 v7, 0xffff0000, v9
	v_fmac_f32_e32 v6, v7, v7
	v_lshlrev_b32_e32 v7, 16, v2
	v_and_b32_e32 v2, 0xffff0000, v2
	v_mul_f32_e32 v2, v2, v2
	v_fmac_f32_e32 v2, v7, v7
	v_lshlrev_b32_e32 v7, 16, v3
	v_fmac_f32_e32 v2, v7, v7
	v_and_b32_e32 v3, 0xffff0000, v3
	v_fmac_f32_e32 v2, v3, v3
	v_lshlrev_b32_e32 v3, 16, v4
	v_fmac_f32_e32 v2, v3, v3
	v_and_b32_e32 v3, 0xffff0000, v4
	v_fmac_f32_e32 v2, v3, v3
	v_lshlrev_b32_e32 v3, 16, v5
	v_fmac_f32_e32 v2, v3, v3
	v_and_b32_e32 v3, 0xffff0000, v5
	v_fmac_f32_e32 v2, v3, v3
	v_add_f32_e32 v2, v6, v2
	ds_bpermute_b32 v0, v0, v2
	s_waitcnt lgkmcnt(0)
	v_add_f32_e32 v0, v2, v0
	ds_bpermute_b32 v2, v42, v0
	s_waitcnt lgkmcnt(0)
	v_add_f32_e32 v0, v0, v2
	ds_bpermute_b32 v2, v43, v0
	s_waitcnt lgkmcnt(0)
	v_add_f32_e32 v0, v0, v2
	ds_bpermute_b32 v2, v44, v0
	s_waitcnt lgkmcnt(0)
	v_add_f32_e32 v0, v0, v2
	ds_bpermute_b32 v2, v45, v0
	s_waitcnt lgkmcnt(0)
	v_add_f32_e32 v0, v0, v2
	ds_bpermute_b32 v2, v46, v0
	s_and_saveexec_b64 s[4:5], vcc
	s_cbranch_execz .LBB0_703
	s_waitcnt lgkmcnt(0)
	v_add_f32_e32 v0, v0, v2
	v_fmamk_f32 v0, v0, 0x3a800000, v241
	s_mov_b32 s8, 0x800000
	v_mul_f32_e32 v2, 0x4b800000, v0
	v_cmp_gt_f32_e32 vcc, s8, v0
	s_nop 1
	v_cndmask_b32_e32 v0, v0, v2, vcc
	v_rsq_f32_e32 v0, v0
	s_nop 0
	v_mul_f32_e32 v2, 0x45800000, v0
	v_cndmask_b32_e32 v0, v0, v2, vcc
	ds_write_b32 v47, v0 offset:32780
	s_branch .LBB0_703
	s_nop 0
	s_nop 0
	s_nop 0
	s_nop 0
	s_nop 0
	s_nop 0
	s_nop 0
	s_nop 0
	s_nop 0
	s_nop 0
	s_nop 0
	s_nop 0
	s_nop 0
	s_nop 0
	s_nop 0
